# P5 filter_phase: one L2 touch load per thread for the NEXT item's KRAW lines (real loads then hit L2), wait vmcnt(1); on top of v46
# baseline (speedup 1.0000x reference)
; __device__ __forceinline__ int lnd(int x) { asm volatile("" : "+v"(x)); return x; }
; __device__ __forceinline__ void filter_phase(const Args& a, LAS unsigned char* lds, int bid, int G, int tid) {
;     ...
;     for (int it = bid; it < 1536; it += G) {
;         const int grp = it >= 768, c = it - grp * 768, L = grp ? LS : LP;
;         const float* kf = KR + (size_t)c * (LP + LS) + grp * LP; const float* kb = kf + (size_t)768 * (LP + LS);
;         cf2 v[32]; float asum = 0.f;
;         { const int tl = lnd(tid);
; #pragma unroll
;           for (int e = 0; e < 32; ++e) {
;             const int i = tl + 512 * e; float val = 0.f;
;             if (e < 16) { if (i < L) val = kf[i]; } else { const int tp = 16384 - i; if (tp >= 1 && tp <= L - 1) val = kb[tp]; }
;             v[e].x = val; v[e].y = 0.f; asum += fabsf(val);
;           } }
;         asum = wave_sum(asum);
;         if (lane == 0) red[wave] = asum;
;         __syncthreads();
.LBB0_782:
	s_or_b64 exec, exec, s[4:5]
	s_add_i32 s100, s69, s70
	s_cmpk_gt_i32 s100, 0x2ff
	s_cselect_b32 s101, 0xfffffd00, 0
	s_cselect_b32 s98, 0x8000, 0
	s_add_i32 s101, s101, s100
	s_mul_hi_i32 s99, s101, 0xc000
	s_mul_i32 s101, s101, 0xc000
	s_add_u32 s101, s20, s101
	s_addc_u32 s99, s21, s99
	s_add_u32 s98, s101, s98
	s_addc_u32 s99, s99, 0
	v_and_b32_e32 v146, 0xff, v136
	v_lshrrev_b32_e32 v147, 8, v136
	v_lshlrev_b32_e32 v146, 7, v146
	v_mul_u32_u24_e32 v147, 36, v147
	v_lshl_add_u32 v146, v147, 20, v146
	global_load_dword v148, v146, s[98:99]
	s_waitcnt vmcnt(1)
	v_add_f32_e64 v0, |v6|, |v7|
	v_add_f32_e64 v0, v0, |v8|
	v_add_f32_e64 v0, v0, |v9|
	v_add_f32_e64 v0, v0, |v10|
	v_add_f32_e64 v0, v0, |v11|
	v_add_f32_e64 v0, v0, |v14|
	v_add_f32_e64 v0, v0, |v15|
	v_add_f32_e64 v0, v0, |v16|
	v_add_f32_e64 v0, v0, |v17|
	v_add_f32_e64 v0, v0, |v18|
	v_add_f32_e64 v0, v0, |v19|
	v_add_f32_e64 v0, v0, |v20|
	v_add_f32_e64 v0, v0, |v21|
	v_add_f32_e64 v0, v0, |v22|
	v_add_f32_e64 v0, v0, |v23|
	v_add_f32_e64 v0, v0, |v24|
	v_add_f32_e64 v0, v0, |v25|
	v_add_f32_e64 v0, v0, |v26|
	v_add_f32_e64 v0, v0, |v27|
	v_add_f32_e64 v0, v0, |v28|
	v_add_f32_e64 v0, v0, |v29|
	v_add_f32_e64 v0, v0, |v30|
	v_add_f32_e64 v0, v0, |v31|
	v_add_f32_e64 v0, v0, |v32|
	v_add_f32_e64 v0, v0, |v33|
	v_add_f32_e64 v0, v0, |v34|
	v_add_f32_e64 v0, v0, |v35|
	v_and_b32_e32 v3, 64, v43
	v_add_f32_e64 v0, v0, |v36|
	v_add_u32_e32 v3, 64, v3
	v_xor_b32_e32 v4, 1, v43
	v_add_f32_e64 v0, v0, |v37|
	v_cmp_lt_i32_e32 vcc, v4, v3
	v_add_f32_e64 v0, v0, |v38|
	v_add_f32_e64 v0, v0, |v39|
	v_cndmask_b32_e32 v4, v43, v4, vcc
	v_lshlrev_b32_e32 v4, 2, v4
	ds_bpermute_b32 v4, v4, v0
	s_ashr_i32 s1, s0, 31
	s_waitcnt lgkmcnt(0)
	v_add_f32_e32 v0, v0, v4
	v_xor_b32_e32 v4, 2, v43
	v_cmp_lt_i32_e32 vcc, v4, v3
	s_nop 1
	v_cndmask_b32_e32 v4, v43, v4, vcc
	v_lshlrev_b32_e32 v4, 2, v4
	ds_bpermute_b32 v4, v4, v0
	s_waitcnt lgkmcnt(0)
	v_add_f32_e32 v0, v0, v4
	v_xor_b32_e32 v4, 4, v43
	v_cmp_lt_i32_e32 vcc, v4, v3
	s_nop 1
	v_cndmask_b32_e32 v4, v43, v4, vcc
	v_lshlrev_b32_e32 v4, 2, v4
	ds_bpermute_b32 v4, v4, v0
	s_waitcnt lgkmcnt(0)
	v_add_f32_e32 v0, v0, v4
	v_xor_b32_e32 v4, 8, v43
	v_cmp_lt_i32_e32 vcc, v4, v3
	s_nop 1
	v_cndmask_b32_e32 v4, v43, v4, vcc
	v_lshlrev_b32_e32 v4, 2, v4
	ds_bpermute_b32 v4, v4, v0
	s_waitcnt lgkmcnt(0)
	v_add_f32_e32 v0, v0, v4
	v_xor_b32_e32 v4, 16, v43
	v_cmp_lt_i32_e32 vcc, v4, v3
	s_nop 1
	v_cndmask_b32_e32 v4, v43, v4, vcc
	v_lshlrev_b32_e32 v4, 2, v4
	ds_bpermute_b32 v4, v4, v0
	s_waitcnt lgkmcnt(0)
	v_add_f32_e32 v0, v0, v4
	v_xor_b32_e32 v4, 32, v43
	v_cmp_lt_i32_e32 vcc, v4, v3
	s_nop 1
	v_cndmask_b32_e32 v3, v43, v4, vcc
	v_lshlrev_b32_e32 v3, 2, v3
	ds_bpermute_b32 v3, v3, v0
	s_and_saveexec_b64 s[2:3], s[6:7]
	s_cbranch_execz .LBB0_717
	s_waitcnt lgkmcnt(0)
	v_add_f32_e32 v0, v0, v3
	ds_write_b32 v42, v0
	s_branch .LBB0_717

; #define LAS __attribute__((address_space(3)))
; __device__ __forceinline__ unsigned pk2(float lo, float hi) { return pg8::cvt_pk_bf16(lo, hi); }
; __device__ __forceinline__ int lnd(int x) { asm volatile("" : "+v"(x)); return x; }
; #define FFT_LD(IDX) do { _Pragma("unroll") for (int e = 0; e < 32; ++e) v[e] = X[IDX(tl_, e)]; } while (0)
; #define FFT_ST(IDX) do { _Pragma("unroll") for (int e = 0; e < 32; ++e) X[IDX(tl_, e)] = v[e]; } while (0)
; #define FFT_PASS() const int tl_ = lnd(tid)
; __device__ __forceinline__ void filter_phase(const Args& a, LAS unsigned char* lds, int bid, int G, int tid) {
;     LAS f32x2v* X = (LAS f32x2v*)lds;
;     LAS float* red = (LAS float*)(lds + 131072);
;     const float* KR = (const float*)(a.ws + WS_KRAW);
;     unsigned* KS = (unsigned*)(a.ws + WS_KSPEC);
;     const int lane = tid & 63, wave = tid >> 6;
;     for (int it = bid; it < 1536; it += G) {
;         const int grp = it >= 768, c = it - grp * 768, L = grp ? LS : LP;
;         const float* kf = KR + (size_t)c * (LP + LS) + grp * LP; const float* kb = kf + (size_t)768 * (LP + LS);
;         cf2 v[32]; float asum = 0.f;
;         { const int tl = lnd(tid);
; #pragma unroll
;           for (int e = 0; e < 32; ++e) {
;             const int i = tl + 512 * e; float val = 0.f;
;             if (e < 16) { if (i < L) val = kf[i]; } else { const int tp = 16384 - i; if (tp >= 1 && tp <= L - 1) val = kb[tp]; }
;             v[e].x = val; v[e].y = 0.f; asum += fabsf(val);
;           } }
;         asum = wave_sum(asum);
;         if (lane == 0) red[wave] = asum;
;         __syncthreads();
;         float tot = 0.f;
; #pragma unroll
;         for (int w = 0; w < 8; ++w) tot += red[w];
;         const float sc = 1.0f / (tot * 16384.0f), dd = a.in[I_HYD][c] * (1.0f / 16384.0f);
;         { FFT_PASS(); dif_stages<5, 0>(v, tl_, 9); FFT_ST(fft_pA); } __syncthreads();
;         { FFT_PASS(); FFT_LD(fft_pB); dif_stages<5, 0>(v, tl_ & 15, 4); FFT_ST(fft_pB); } __syncthreads();
;         { FFT_PASS(); FFT_LD(fft_pC); dif_stages<4, 0, true>(v, 0, 0); dif_stages<4, 16, true>(v, 0, 0);
;           unsigned* kp = KS + (size_t)it * 16384 + tl_;
; #pragma unroll
;           for (int e = 0; e < 32; ++e) kp[e * 512] = pk2(v[e].x * sc + dd, v[e].y * sc); }
;         __syncthreads();
;     }
; }
	.amdhsa_kernel _Z6mk_fwdILi65535EEv4Args
		.amdhsa_group_segment_fixed_size 0
		.amdhsa_private_segment_fixed_size 0
		.amdhsa_kernarg_size 504
		.amdhsa_user_sgpr_count 2
		.amdhsa_user_sgpr_dispatch_ptr 0
		.amdhsa_user_sgpr_queue_ptr 0
		.amdhsa_user_sgpr_kernarg_segment_ptr 1
		.amdhsa_user_sgpr_dispatch_id 0
		.amdhsa_user_sgpr_kernarg_preload_length 0
		.amdhsa_user_sgpr_kernarg_preload_offset 0
		.amdhsa_user_sgpr_private_segment_size 0
		.amdhsa_uses_dynamic_stack 0
		.amdhsa_enable_private_segment 0
		.amdhsa_system_sgpr_workgroup_id_x 1
		.amdhsa_system_sgpr_workgroup_id_y 0
		.amdhsa_system_sgpr_workgroup_id_z 0
		.amdhsa_system_sgpr_workgroup_info 0
		.amdhsa_system_vgpr_workitem_id 2
		.amdhsa_next_free_vgpr 256
		.amdhsa_next_free_sgpr 102
		.amdhsa_accum_offset 256
		.amdhsa_reserve_vcc 1
		.amdhsa_float_round_mode_32 0
		.amdhsa_float_round_mode_16_64 0
		.amdhsa_float_denorm_mode_32 3
		.amdhsa_float_denorm_mode_16_64 3
		.amdhsa_dx10_clamp 1
		.amdhsa_ieee_mode 1
		.amdhsa_fp16_overflow 0
		.amdhsa_tg_split 0
		.amdhsa_exception_fp_ieee_invalid_op 0
		.amdhsa_exception_fp_denorm_src 0
		.amdhsa_exception_fp_ieee_div_zero 0
		.amdhsa_exception_fp_ieee_overflow 0
		.amdhsa_exception_fp_ieee_underflow 0
		.amdhsa_exception_fp_ieee_inexact 0
		.amdhsa_exception_int_div_zero 0
	.end_amdhsa_kernel

; #define LAS __attribute__((address_space(3)))
; __device__ __forceinline__ unsigned pk2(float lo, float hi) { return pg8::cvt_pk_bf16(lo, hi); }
; __device__ __forceinline__ int lnd(int x) { asm volatile("" : "+v"(x)); return x; }
; #define FFT_LD(IDX) do { _Pragma("unroll") for (int e = 0; e < 32; ++e) v[e] = X[IDX(tl_, e)]; } while (0)
; #define FFT_ST(IDX) do { _Pragma("unroll") for (int e = 0; e < 32; ++e) X[IDX(tl_, e)] = v[e]; } while (0)
; #define FFT_PASS() const int tl_ = lnd(tid)
; __device__ __forceinline__ void filter_phase(const Args& a, LAS unsigned char* lds, int bid, int G, int tid) {
;     LAS f32x2v* X = (LAS f32x2v*)lds;
;     LAS float* red = (LAS float*)(lds + 131072);
;     const float* KR = (const float*)(a.ws + WS_KRAW);
;     unsigned* KS = (unsigned*)(a.ws + WS_KSPEC);
;     const int lane = tid & 63, wave = tid >> 6;
;     for (int it = bid; it < 1536; it += G) {
;         const int grp = it >= 768, c = it - grp * 768, L = grp ? LS : LP;
;         const float* kf = KR + (size_t)c * (LP + LS) + grp * LP; const float* kb = kf + (size_t)768 * (LP + LS);
;         cf2 v[32]; float asum = 0.f;
;         { const int tl = lnd(tid);
; #pragma unroll
;           for (int e = 0; e < 32; ++e) {
;             const int i = tl + 512 * e; float val = 0.f;
;             if (e < 16) { if (i < L) val = kf[i]; } else { const int tp = 16384 - i; if (tp >= 1 && tp <= L - 1) val = kb[tp]; }
;             v[e].x = val; v[e].y = 0.f; asum += fabsf(val);
;           } }
;         asum = wave_sum(asum);
;         if (lane == 0) red[wave] = asum;
;         __syncthreads();
;         float tot = 0.f;
; #pragma unroll
;         for (int w = 0; w < 8; ++w) tot += red[w];
;         const float sc = 1.0f / (tot * 16384.0f), dd = a.in[I_HYD][c] * (1.0f / 16384.0f);
;         { FFT_PASS(); dif_stages<5, 0>(v, tl_, 9); FFT_ST(fft_pA); } __syncthreads();
;         { FFT_PASS(); FFT_LD(fft_pB); dif_stages<5, 0>(v, tl_ & 15, 4); FFT_ST(fft_pB); } __syncthreads();
;         { FFT_PASS(); FFT_LD(fft_pC); dif_stages<4, 0, true>(v, 0, 0); dif_stages<4, 16, true>(v, 0, 0);
;           unsigned* kp = KS + (size_t)it * 16384 + tl_;
; #pragma unroll
;           for (int e = 0; e < 32; ++e) kp[e * 512] = pk2(v[e].x * sc + dd, v[e].y * sc); }
;         __syncthreads();
;     }
; }
amdhsa.kernels:
  - .agpr_count:     0
    .args:
      - .offset:         0
        .size:           248
        .value_kind:     by_value
      - .offset:         248
        .size:           4
        .value_kind:     hidden_block_count_x
      - .offset:         252
        .size:           4
        .value_kind:     hidden_block_count_y
      - .offset:         256
        .size:           4
        .value_kind:     hidden_block_count_z
      - .offset:         260
        .size:           2
        .value_kind:     hidden_group_size_x
      - .offset:         262
        .size:           2
        .value_kind:     hidden_group_size_y
      - .offset:         264
        .size:           2
        .value_kind:     hidden_group_size_z
      - .offset:         266
        .size:           2
        .value_kind:     hidden_remainder_x
      - .offset:         268
        .size:           2
        .value_kind:     hidden_remainder_y
      - .offset:         270
        .size:           2
        .value_kind:     hidden_remainder_z
      - .offset:         288
        .size:           8
        .value_kind:     hidden_global_offset_x
      - .offset:         296
        .size:           8
        .value_kind:     hidden_global_offset_y
      - .offset:         304
        .size:           8
        .value_kind:     hidden_global_offset_z
      - .offset:         312
        .size:           2
        .value_kind:     hidden_grid_dims
      - .offset:         336
        .size:           8
        .value_kind:     hidden_multigrid_sync_arg
      - .offset:         368
        .size:           4
        .value_kind:     hidden_dynamic_lds_size
    .group_segment_fixed_size: 0
    .kernarg_segment_align: 8
    .kernarg_segment_size: 504
    .language:       OpenCL C
    .language_version:
      - 2
      - 0
    .max_flat_workgroup_size: 512
    .name:           _Z6mk_fwdILi65535EEv4Args
    .private_segment_fixed_size: 0
    .sgpr_count:     108
    .sgpr_spill_count: 82
    .symbol:         _Z6mk_fwdILi65535EEv4Args.kd
    .uniform_work_group_size: 1
    .uses_dynamic_stack: false
    .vgpr_count:     256
    .vgpr_spill_count: 0
    .wavefront_size: 64
